# attention: static s_setprio 1 for waves 0-3 instead (mirror of v36's raise), on top of v37
# baseline (speedup 1.0000x reference)
; __device__ __forceinline__ void attn_phase(const Ctx& c, int j, char* lds) {
;     ...
;     for (int u = blockIdx.x; u < 1024 + 224; u += c.G) {
;         if (u < 1024) {
;             const int r = u >> 8, w = u & 255, x = w & 7, slot = w >> 3, pair = r * 8 + x;
;             const int b = pair >> 3, kvh = pair & 7, h = kvh * 2 + (slot >> 4), qb = slot & 15;
;             att::attn_unit(P, O, b, h, kvh, qb, false, 0, 65, nullptr, nullptr, QNW, RTAB, lds);
;         } else {
;             const int idx = u - 1024, pair = idx & 31, p = idx >> 5;
;             att::attn_unit(P, O, pair >> 3, 0, pair & 7, 0, true, p == 0 ? 0 : 11 + 9 * (p - 1), p == 0 ? 11 : 9, PART + (size_t)(pair * 7 + p) * (32 * 132), CNT + pair, QNW, RTAB, lds);
;         }
;     }
.LBB0_267:
	s_cmp_lt_i32 s74, 4
	s_cselect_b64 s[0:1], -1, 0
	s_cmp_gt_i32 s75, 3
	s_cselect_b64 s[2:3], -1, 0
	s_and_b64 s[0:1], s[0:1], s[2:3]
	s_andn2_b64 vcc, exec, s[0:1]
	v_writelane_b32 v254, s63, 29
	s_cbranch_vccnz .LBB0_377
	v_readfirstlane_b32 s98, v200
	s_nop 3
	s_lshr_b32 s98, s98, 6
	s_cmp_lt_u32 s98, 4
	s_cbranch_scc0 .Lattn_prlo_a
	s_setprio 1

; __device__ __forceinline__ void attn_unit(const bf16* __restrict__ P, unsigned short* __restrict__ Ob, int b, int h, int kvh, int qb, bool meta, int jt0, int ntl, float* part, unsigned* cnt, const float* __restrict__ qnw, const float2* __restrict__ rtab, char* lds) {
;     ...
;   __syncthreads();
; __device__ __forceinline__ void attn_phase(const Ctx& c, int j, char* lds) {
;     ...
;     for (int u = blockIdx.x; u < 1024 + 224; u += c.G) {
;         if (u < 1024) {
;             const int r = u >> 8, w = u & 255, x = w & 7, slot = w >> 3, pair = r * 8 + x;
;             const int b = pair >> 3, kvh = pair & 7, h = kvh * 2 + (slot >> 4), qb = slot & 15;
;             att::attn_unit(P, O, b, h, kvh, qb, false, 0, 65, nullptr, nullptr, QNW, RTAB, lds);
;         } else {
;             const int idx = u - 1024, pair = idx & 31, p = idx >> 5;
;             att::attn_unit(P, O, pair >> 3, 0, pair & 7, 0, true, p == 0 ? 0 : 11 + 9 * (p - 1), p == 0 ? 11 : 9, PART + (size_t)(pair * 7 + p) * (32 * 132), CNT + pair, QNW, RTAB, lds);
;         }
;     }
.LBB0_376:
	s_or_b64 exec, exec, s[2:3]
	s_waitcnt lgkmcnt(0)
	s_barrier
	s_nop 0
	s_nop 0
	s_nop 0
	s_nop 0
	s_nop 0
	s_nop 0
	s_nop 0
	s_nop 0
	s_nop 0
	s_nop 0
	s_nop 0
	s_nop 0
	s_nop 0
	s_nop 0
	s_setprio 0
	s_nop 0
	s_nop 0
	s_nop 0
	s_nop 0
	s_nop 0
	s_nop 0
	s_nop 0
	s_nop 0
	s_nop 0
	s_nop 0
	s_nop 0
	s_nop 0
	s_nop 0
	s_nop 0
	s_nop 0

; __device__ __forceinline__ void attn_phase(const Ctx& c, int j, char* lds) {
;     ...
;     for (int u = blockIdx.x; u < 1024 + 224; u += c.G) {
;         if (u < 1024) {
;             const int r = u >> 8, w = u & 255, x = w & 7, slot = w >> 3, pair = r * 8 + x;
;             const int b = pair >> 3, kvh = pair & 7, h = kvh * 2 + (slot >> 4), qb = slot & 15;
;             att::attn_unit(P, O, b, h, kvh, qb, false, 0, 65, nullptr, nullptr, QNW, RTAB, lds);
;         } else {
;             const int idx = u - 1024, pair = idx & 31, p = idx >> 5;
;             att::attn_unit(P, O, pair >> 3, 0, pair & 7, 0, true, p == 0 ? 0 : 11 + 9 * (p - 1), p == 0 ? 11 : 9, PART + (size_t)(pair * 7 + p) * (32 * 132), CNT + pair, QNW, RTAB, lds);
;         }
;     }
.LBB0_1231:
	s_cmp_lt_i32 s74, 20
	s_cselect_b64 s[0:1], -1, 0
	s_cmp_gt_i32 s75, 19
	v_writelane_b32 v254, s68, 30
	s_cselect_b64 s[2:3], -1, 0
	s_and_b64 s[0:1], s[0:1], s[2:3]
	v_writelane_b32 v254, s69, 31
	v_writelane_b32 v254, s70, 32
	v_writelane_b32 v254, s71, 33
	v_writelane_b32 v254, s72, 34
	v_writelane_b32 v254, s73, 35
	s_andn2_b64 vcc, exec, s[0:1]
	v_writelane_b32 v254, s74, 36
	v_writelane_b32 v254, s75, 37
	s_cbranch_vccnz .LBB0_1341
	v_readfirstlane_b32 s98, v200
	s_nop 3
	s_lshr_b32 s98, s98, 6
	s_cmp_lt_u32 s98, 4
	s_cbranch_scc0 .Lattn_prlo_b
	s_setprio 1
